# same as previous best but the SwiGLU epilogue drains with vmcnt(0) before copying/issuing the prefetched row scales (no reliance on completion order between LDS-DMA and VGPR loads)
# baseline (speedup 1.0000x reference)
; __device__ __forceinline__ unsigned cvt_pk_bf16(float lo, float hi) { unsigned r; asm volatile("v_cvt_pk_bf16_f32 %0, %1, %2" : "=v"(r) : "v"(lo), "v"(hi)); return r; }
; __device__ __forceinline__ float fast_sigmoid(float x) { return __builtin_amdgcn_rcpf(1.f + __builtin_amdgcn_exp2f(-1.4426950408889634f * x)); }
; __device__ __forceinline__ void row_scales_direct(const float* rs, int row0, float (&rsv)[2][4]) {
; #pragma unroll
;     for (int ai = 0; ai < 2; ++ai)
; #pragma unroll
;         for (int m = 0; m < 4; ++m) rsv[ai][m] = ((const __attribute__((address_space(1))) float*)rs)[row0 + ai * HALF + m * 16];
; }
;     __device__ __forceinline__ void operator()(const f32x4 (&acc)[2][2][4][2], const Unit& u, int wr, int wc, int fr, int fq) const {
;         const int row0 = u.pm * BM + wr * 64 + fr, col0 = u.pn * HALF + wc * 32 + 8 * fq;
;         float rsv[2][4]; row_scales_direct(ssq, row0, rsv);
; #pragma unroll
;         for (int ai = 0; ai < 2; ++ai)
; #pragma unroll
;             for (int m = 0; m < 4; ++m) { float o[8];
; #pragma unroll
;                 for (int n = 0; n < 2; ++n)
; #pragma unroll
;                     for (int j = 0; j < 4; ++j) { const float g = acc[ai][0][m][n][j] * rsv[ai][m], up = acc[ai][1][m][n][j] * rsv[ai][m]; o[n * 4 + j] = g * fast_sigmoid(g) * up; }
;                 u32x4 w; w.x = cvt_pk_bf16(o[0], o[1]); w.y = cvt_pk_bf16(o[2], o[3]); w.z = cvt_pk_bf16(o[4], o[5]); w.w = cvt_pk_bf16(o[6], o[7]);
;                 *(u32x4*)(H + (size_t)(row0 + ai * HALF + m * 16) * ldh + col0) = w; }
.LBB0_238:
	s_waitcnt vmcnt(0)
	v_mov_b32_e32 v242, v234
	v_mov_b32_e32 v243, v235
	v_mov_b32_e32 v244, v236
	v_mov_b32_e32 v245, v237
	v_mov_b32_e32 v246, v238
	v_mov_b32_e32 v247, v239
	v_mov_b32_e32 v250, v240
	v_mov_b32_e32 v251, v241
	s_and_b64 s[38:39], s[40:41], exec
	s_cselect_b32 s38, s54, s81
	v_lshl_add_u32 v166, s38, 8, v141
	v_ashrrev_i32_e32 v167, 31, v166
	v_lshl_add_u64 v[168:169], v[166:167], 2, s[42:43]
	global_load_dword v234, v[168:169], off
	global_load_dword v235, v[168:169], off offset:64
	global_load_dword v236, v[168:169], off offset:128
	global_load_dword v237, v[168:169], off offset:192
	global_load_dword v238, v[168:169], off offset:512
	global_load_dword v239, v[168:169], off offset:576
	global_load_dword v240, v[168:169], off offset:640
	global_load_dword v241, v[168:169], off offset:704
	v_lshl_add_u32 v138, s81, 8, v141
	v_lshl_or_b32 v170, s77, 7, v145
	v_ashrrev_i32_e32 v171, 31, v170
	s_movk_i32 s53, 0x2c00
	v_mov_b64_e32 v[160:161], s[48:49]
	v_lshlrev_b64 v[162:163], 1, v[170:171]
	v_mul_f32_e32 v156, 0xbfb8aa3b, v242
	v_mul_f32_e32 v158, v242, v242
	v_rcp_f32_e32 v157, v158
	v_mad_i64_i32 v[164:165], s[38:39], v138, s53, v[160:161]
	v_lshl_add_u64 v[164:165], v[164:165], 0, v[162:163]
	v_mul_f32_e32 v148, v124, v156
	v_mul_f32_e32 v149, v125, v156
	v_mul_f32_e32 v150, v126, v156
	v_mul_f32_e32 v151, v127, v156
	v_mul_f32_e32 v152, v116, v156
	v_mul_f32_e32 v153, v117, v156
	v_mul_f32_e32 v154, v118, v156
	v_mul_f32_e32 v155, v119, v156
	v_exp_f32_e32 v148, v148
	v_exp_f32_e32 v149, v149
	v_exp_f32_e32 v150, v150
	v_exp_f32_e32 v151, v151
	v_exp_f32_e32 v152, v152
	v_exp_f32_e32 v153, v153
	v_exp_f32_e32 v154, v154
	v_exp_f32_e32 v155, v155
	v_fma_f32 v148, v148, v157, v157
	v_fma_f32 v149, v149, v157, v157
	v_fma_f32 v150, v150, v157, v157
	v_fma_f32 v151, v151, v157, v157
	v_fma_f32 v152, v152, v157, v157
	v_fma_f32 v153, v153, v157, v157
	v_fma_f32 v154, v154, v157, v157
	v_fma_f32 v155, v155, v157, v157
	v_rcp_f32_e32 v148, v148
	v_rcp_f32_e32 v149, v149
	v_rcp_f32_e32 v150, v150
	v_rcp_f32_e32 v151, v151
	v_rcp_f32_e32 v152, v152
	v_rcp_f32_e32 v153, v153
	v_rcp_f32_e32 v154, v154
	v_rcp_f32_e32 v155, v155
	v_mul_f32_e32 v124, v124, v120
	v_mul_f32_e32 v125, v125, v121
	v_mul_f32_e32 v126, v126, v122
	v_mul_f32_e32 v127, v127, v123
	v_mul_f32_e32 v116, v116, v112
	v_mul_f32_e32 v117, v117, v113
	v_mul_f32_e32 v118, v118, v114
	v_mul_f32_e32 v119, v119, v115
	v_mul_f32_e32 v124, v124, v148
	v_mul_f32_e32 v125, v125, v149
	v_mul_f32_e32 v126, v126, v150
	v_mul_f32_e32 v127, v127, v151
	v_mul_f32_e32 v116, v116, v152
	v_mul_f32_e32 v117, v117, v153
	v_mul_f32_e32 v118, v118, v154
	v_mul_f32_e32 v119, v119, v155
	v_cvt_pk_bf16_f32 v120, v124, v125
	v_cvt_pk_bf16_f32 v121, v126, v127
	v_cvt_pk_bf16_f32 v122, v116, v117
	v_cvt_pk_bf16_f32 v123, v118, v119
	global_store_dwordx4 v[164:165], v[120:123], off
	v_mul_f32_e32 v156, 0xbfb8aa3b, v243
	v_mul_f32_e32 v158, v243, v243
	v_rcp_f32_e32 v157, v158
	v_add_u32_e32 v166, 0x10, v138
	v_mad_i64_i32 v[164:165], s[38:39], v166, s53, v[160:161]
	v_lshl_add_u64 v[164:165], v[164:165], 0, v[162:163]
	v_mul_f32_e32 v148, v108, v156
	v_mul_f32_e32 v149, v109, v156
	v_mul_f32_e32 v150, v110, v156
	v_mul_f32_e32 v151, v111, v156
	v_mul_f32_e32 v152, v100, v156
	v_mul_f32_e32 v153, v101, v156
	v_mul_f32_e32 v154, v102, v156
	v_mul_f32_e32 v155, v103, v156
	v_exp_f32_e32 v148, v148
	v_exp_f32_e32 v149, v149
	v_exp_f32_e32 v150, v150
	v_exp_f32_e32 v151, v151
	v_exp_f32_e32 v152, v152
	v_exp_f32_e32 v153, v153
	v_exp_f32_e32 v154, v154
	v_exp_f32_e32 v155, v155
	v_fma_f32 v148, v148, v157, v157
	v_fma_f32 v149, v149, v157, v157
	v_fma_f32 v150, v150, v157, v157
	v_fma_f32 v151, v151, v157, v157
	v_fma_f32 v152, v152, v157, v157
	v_fma_f32 v153, v153, v157, v157
	v_fma_f32 v154, v154, v157, v157
	v_fma_f32 v155, v155, v157, v157
	v_rcp_f32_e32 v148, v148
	v_rcp_f32_e32 v149, v149
	v_rcp_f32_e32 v150, v150
	v_rcp_f32_e32 v151, v151
	v_rcp_f32_e32 v152, v152
	v_rcp_f32_e32 v153, v153
	v_rcp_f32_e32 v154, v154
	v_rcp_f32_e32 v155, v155
	v_mul_f32_e32 v108, v108, v104
	v_mul_f32_e32 v109, v109, v105
	v_mul_f32_e32 v110, v110, v106
	v_mul_f32_e32 v111, v111, v107
	v_mul_f32_e32 v100, v100, v96
	v_mul_f32_e32 v101, v101, v97
	v_mul_f32_e32 v102, v102, v98
	v_mul_f32_e32 v103, v103, v99
	v_mul_f32_e32 v108, v108, v148
	v_mul_f32_e32 v109, v109, v149
	v_mul_f32_e32 v110, v110, v150
	v_mul_f32_e32 v111, v111, v151
	v_mul_f32_e32 v100, v100, v152
	v_mul_f32_e32 v101, v101, v153
	v_mul_f32_e32 v102, v102, v154
	v_mul_f32_e32 v103, v103, v155
	v_cvt_pk_bf16_f32 v104, v108, v109
	v_cvt_pk_bf16_f32 v105, v110, v111
	v_cvt_pk_bf16_f32 v106, v100, v101
	v_cvt_pk_bf16_f32 v107, v102, v103
	global_store_dwordx4 v[164:165], v[104:107], off
	v_mul_f32_e32 v156, 0xbfb8aa3b, v244
	v_mul_f32_e32 v158, v244, v244
	v_rcp_f32_e32 v157, v158
	v_add_u32_e32 v166, 0x20, v138
	v_mad_i64_i32 v[164:165], s[38:39], v166, s53, v[160:161]
	v_lshl_add_u64 v[164:165], v[164:165], 0, v[162:163]
	v_mul_f32_e32 v148, v92, v156
	v_mul_f32_e32 v149, v93, v156
	v_mul_f32_e32 v150, v94, v156
	v_mul_f32_e32 v151, v95, v156
	v_mul_f32_e32 v152, v84, v156
	v_mul_f32_e32 v153, v85, v156
	v_mul_f32_e32 v154, v86, v156
	v_mul_f32_e32 v155, v87, v156
	v_exp_f32_e32 v148, v148
	v_exp_f32_e32 v149, v149
	v_exp_f32_e32 v150, v150
	v_exp_f32_e32 v151, v151
	v_exp_f32_e32 v152, v152
	v_exp_f32_e32 v153, v153
	v_exp_f32_e32 v154, v154
	v_exp_f32_e32 v155, v155
	v_fma_f32 v148, v148, v157, v157
	v_fma_f32 v149, v149, v157, v157
	v_fma_f32 v150, v150, v157, v157
	v_fma_f32 v151, v151, v157, v157
	v_fma_f32 v152, v152, v157, v157
; __device__ __forceinline__ unsigned cvt_pk_bf16(float lo, float hi) { unsigned r; asm volatile("v_cvt_pk_bf16_f32 %0, %1, %2" : "=v"(r) : "v"(lo), "v"(hi)); return r; }
; __device__ __forceinline__ float fast_sigmoid(float x) { return __builtin_amdgcn_rcpf(1.f + __builtin_amdgcn_exp2f(-1.4426950408889634f * x)); }
;     __device__ __forceinline__ void operator()(const f32x4 (&acc)[2][2][4][2], const Unit& u, int wr, int wc, int fr, int fq) const {
;     ...
;             for (int m = 0; m < 4; ++m) { float o[8];
; #pragma unroll
;                 for (int n = 0; n < 2; ++n)
; #pragma unroll
;                     for (int j = 0; j < 4; ++j) { const float g = acc[ai][0][m][n][j] * rsv[ai][m], up = acc[ai][1][m][n][j] * rsv[ai][m]; o[n * 4 + j] = g * fast_sigmoid(g) * up; }
;                 u32x4 w; w.x = cvt_pk_bf16(o[0], o[1]); w.y = cvt_pk_bf16(o[2], o[3]); w.z = cvt_pk_bf16(o[4], o[5]); w.w = cvt_pk_bf16(o[6], o[7]);
;                 *(u32x4*)(H + (size_t)(row0 + ai * HALF + m * 16) * ldh + col0) = w; }
	v_fma_f32 v153, v153, v157, v157
	v_fma_f32 v154, v154, v157, v157
	v_fma_f32 v155, v155, v157, v157
	v_rcp_f32_e32 v148, v148
	v_rcp_f32_e32 v149, v149
	v_rcp_f32_e32 v150, v150
	v_rcp_f32_e32 v151, v151
	v_rcp_f32_e32 v152, v152
	v_rcp_f32_e32 v153, v153
	v_rcp_f32_e32 v154, v154
	v_rcp_f32_e32 v155, v155
	v_mul_f32_e32 v92, v92, v88
	v_mul_f32_e32 v93, v93, v89
	v_mul_f32_e32 v94, v94, v90
	v_mul_f32_e32 v95, v95, v91
	v_mul_f32_e32 v84, v84, v80
	v_mul_f32_e32 v85, v85, v81
	v_mul_f32_e32 v86, v86, v82
	v_mul_f32_e32 v87, v87, v83
	v_mul_f32_e32 v92, v92, v148
	v_mul_f32_e32 v93, v93, v149
	v_mul_f32_e32 v94, v94, v150
	v_mul_f32_e32 v95, v95, v151
	v_mul_f32_e32 v84, v84, v152
	v_mul_f32_e32 v85, v85, v153
	v_mul_f32_e32 v86, v86, v154
	v_mul_f32_e32 v87, v87, v155
	v_cvt_pk_bf16_f32 v88, v92, v93
	v_cvt_pk_bf16_f32 v89, v94, v95
	v_cvt_pk_bf16_f32 v90, v84, v85
	v_cvt_pk_bf16_f32 v91, v86, v87
	global_store_dwordx4 v[164:165], v[88:91], off
	v_mul_f32_e32 v156, 0xbfb8aa3b, v245
	v_mul_f32_e32 v158, v245, v245
	v_rcp_f32_e32 v157, v158
	v_add_u32_e32 v166, 0x30, v138
	v_mad_i64_i32 v[164:165], s[38:39], v166, s53, v[160:161]
	v_lshl_add_u64 v[164:165], v[164:165], 0, v[162:163]
	v_mul_f32_e32 v148, v76, v156
	v_mul_f32_e32 v149, v77, v156
	v_mul_f32_e32 v150, v78, v156
	v_mul_f32_e32 v151, v79, v156
	v_mul_f32_e32 v152, v68, v156
	v_mul_f32_e32 v153, v69, v156
	v_mul_f32_e32 v154, v70, v156
	v_mul_f32_e32 v155, v71, v156
	v_exp_f32_e32 v148, v148
	v_exp_f32_e32 v149, v149
	v_exp_f32_e32 v150, v150
	v_exp_f32_e32 v151, v151
	v_exp_f32_e32 v152, v152
	v_exp_f32_e32 v153, v153
	v_exp_f32_e32 v154, v154
	v_exp_f32_e32 v155, v155
	v_fma_f32 v148, v148, v157, v157
	v_fma_f32 v149, v149, v157, v157
	v_fma_f32 v150, v150, v157, v157
	v_fma_f32 v151, v151, v157, v157
	v_fma_f32 v152, v152, v157, v157
	v_fma_f32 v153, v153, v157, v157
	v_fma_f32 v154, v154, v157, v157
	v_fma_f32 v155, v155, v157, v157
	v_rcp_f32_e32 v148, v148
	v_rcp_f32_e32 v149, v149
	v_rcp_f32_e32 v150, v150
	v_rcp_f32_e32 v151, v151
	v_rcp_f32_e32 v152, v152
	v_rcp_f32_e32 v153, v153
	v_rcp_f32_e32 v154, v154
	v_rcp_f32_e32 v155, v155
	v_mul_f32_e32 v76, v76, v72
	v_mul_f32_e32 v77, v77, v73
	v_mul_f32_e32 v78, v78, v74
	v_mul_f32_e32 v79, v79, v75
	v_mul_f32_e32 v68, v68, v64
	v_mul_f32_e32 v69, v69, v65
	v_mul_f32_e32 v70, v70, v66
	v_mul_f32_e32 v71, v71, v67
	v_mul_f32_e32 v76, v76, v148
	v_mul_f32_e32 v77, v77, v149
	v_mul_f32_e32 v78, v78, v150
	v_mul_f32_e32 v79, v79, v151
	v_mul_f32_e32 v68, v68, v152
	v_mul_f32_e32 v69, v69, v153
	v_mul_f32_e32 v70, v70, v154
	v_mul_f32_e32 v71, v71, v155
	v_cvt_pk_bf16_f32 v72, v76, v77
	v_cvt_pk_bf16_f32 v73, v78, v79
	v_cvt_pk_bf16_f32 v74, v68, v69
	v_cvt_pk_bf16_f32 v75, v70, v71
	global_store_dwordx4 v[164:165], v[72:75], off
	v_mul_f32_e32 v156, 0xbfb8aa3b, v246
	v_mul_f32_e32 v158, v246, v246
	v_rcp_f32_e32 v157, v158
	v_add_u32_e32 v166, 0x80, v138
	v_mad_i64_i32 v[164:165], s[38:39], v166, s53, v[160:161]
	v_lshl_add_u64 v[164:165], v[164:165], 0, v[162:163]
	v_mul_f32_e32 v148, v60, v156
	v_mul_f32_e32 v149, v61, v156
	v_mul_f32_e32 v150, v62, v156
	v_mul_f32_e32 v151, v63, v156
	v_mul_f32_e32 v152, v52, v156
	v_mul_f32_e32 v153, v53, v156
	v_mul_f32_e32 v154, v54, v156
	v_mul_f32_e32 v155, v55, v156
	v_exp_f32_e32 v148, v148
	v_exp_f32_e32 v149, v149
	v_exp_f32_e32 v150, v150
	v_exp_f32_e32 v151, v151
	v_exp_f32_e32 v152, v152
	v_exp_f32_e32 v153, v153
	v_exp_f32_e32 v154, v154
	v_exp_f32_e32 v155, v155
	v_fma_f32 v148, v148, v157, v157
	v_fma_f32 v149, v149, v157, v157
	v_fma_f32 v150, v150, v157, v157
	v_fma_f32 v151, v151, v157, v157
	v_fma_f32 v152, v152, v157, v157
	v_fma_f32 v153, v153, v157, v157
	v_fma_f32 v154, v154, v157, v157
	v_fma_f32 v155, v155, v157, v157
	v_rcp_f32_e32 v148, v148
	v_rcp_f32_e32 v149, v149
	v_rcp_f32_e32 v150, v150
	v_rcp_f32_e32 v151, v151
	v_rcp_f32_e32 v152, v152
	v_rcp_f32_e32 v153, v153
	v_rcp_f32_e32 v154, v154
	v_rcp_f32_e32 v155, v155
	v_mul_f32_e32 v60, v60, v56
	v_mul_f32_e32 v61, v61, v57
	v_mul_f32_e32 v62, v62, v58
	v_mul_f32_e32 v63, v63, v59
	v_mul_f32_e32 v52, v52, v48
	v_mul_f32_e32 v53, v53, v49
	v_mul_f32_e32 v54, v54, v50
	v_mul_f32_e32 v55, v55, v51
	v_mul_f32_e32 v60, v60, v148
	v_mul_f32_e32 v61, v61, v149
	v_mul_f32_e32 v62, v62, v150
	v_mul_f32_e32 v63, v63, v151
	v_mul_f32_e32 v52, v52, v152
	v_mul_f32_e32 v53, v53, v153
	v_mul_f32_e32 v54, v54, v154
	v_mul_f32_e32 v55, v55, v155
	v_cvt_pk_bf16_f32 v56, v60, v61
	v_cvt_pk_bf16_f32 v57, v62, v63
	v_cvt_pk_bf16_f32 v58, v52, v53
	v_cvt_pk_bf16_f32 v59, v54, v55
	global_store_dwordx4 v[164:165], v[56:59], off
	v_mul_f32_e32 v156, 0xbfb8aa3b, v247
	v_mul_f32_e32 v158, v247, v247
	v_rcp_f32_e32 v157, v158
	v_add_u32_e32 v166, 0x90, v138
	v_mad_i64_i32 v[164:165], s[38:39], v166, s53, v[160:161]
	v_lshl_add_u64 v[164:165], v[164:165], 0, v[162:163]
	v_mul_f32_e32 v148, v44, v156
	v_mul_f32_e32 v149, v45, v156
	v_mul_f32_e32 v150, v46, v156
	v_mul_f32_e32 v151, v47, v156
	v_mul_f32_e32 v152, v36, v156
	v_mul_f32_e32 v153, v37, v156
	v_mul_f32_e32 v154, v38, v156
	v_mul_f32_e32 v155, v39, v156
	v_exp_f32_e32 v148, v148
; __device__ __forceinline__ unsigned cvt_pk_bf16(float lo, float hi) { unsigned r; asm volatile("v_cvt_pk_bf16_f32 %0, %1, %2" : "=v"(r) : "v"(lo), "v"(hi)); return r; }
; __device__ __forceinline__ float fast_sigmoid(float x) { return __builtin_amdgcn_rcpf(1.f + __builtin_amdgcn_exp2f(-1.4426950408889634f * x)); }
; #define PG8_BAR __builtin_amdgcn_s_barrier()
;     __device__ __forceinline__ void operator()(const f32x4 (&acc)[2][2][4][2], const Unit& u, int wr, int wc, int fr, int fq) const {
;     ...
;             for (int m = 0; m < 4; ++m) { float o[8];
; #pragma unroll
;                 for (int n = 0; n < 2; ++n)
; #pragma unroll
;                     for (int j = 0; j < 4; ++j) { const float g = acc[ai][0][m][n][j] * rsv[ai][m], up = acc[ai][1][m][n][j] * rsv[ai][m]; o[n * 4 + j] = g * fast_sigmoid(g) * up; }
;                 u32x4 w; w.x = cvt_pk_bf16(o[0], o[1]); w.y = cvt_pk_bf16(o[2], o[3]); w.z = cvt_pk_bf16(o[4], o[5]); w.w = cvt_pk_bf16(o[6], o[7]);
;                 *(u32x4*)(H + (size_t)(row0 + ai * HALF + m * 16) * ldh + col0) = w; }
; template <class Epi, class Sched, bool ALIGN_EPI = false, bool SP2 = false>
; __device__ __forceinline__ void gemm_phase(PG8_LAS unsigned char* lds, const Gemm g, const Sched& S, const Epi& E, int wave_id) {
;     ...
;         if constexpr (!Epi::AFTER_DRAIN) { E(acc, cur, wr, wc, fr, fq); S.done(cur); }
;         if (!has_next) break;
; #pragma unroll
;         for (int a = 0; a < 2; ++a)
; #pragma unroll
;             for (int b = 0; b < 2; ++b)
; #pragma unroll
;                 for (int m = 0; m < 4; ++m)
; #pragma unroll
;                     for (int n = 0; n < 2; ++n) acc[a][b][m][n] = (f32x4){0.f, 0.f, 0.f, 0.f};
;         cur = nxt; cA = nA; cB = nB; ++ui;
;         if constexpr (ALIGN_EPI) { if (wr == 1) PG8_BAR; }
	v_exp_f32_e32 v149, v149
	v_exp_f32_e32 v150, v150
	v_exp_f32_e32 v151, v151
	v_exp_f32_e32 v152, v152
	v_exp_f32_e32 v153, v153
	v_exp_f32_e32 v154, v154
	v_exp_f32_e32 v155, v155
	v_fma_f32 v148, v148, v157, v157
	v_fma_f32 v149, v149, v157, v157
	v_fma_f32 v150, v150, v157, v157
	v_fma_f32 v151, v151, v157, v157
	v_fma_f32 v152, v152, v157, v157
	v_fma_f32 v153, v153, v157, v157
	v_fma_f32 v154, v154, v157, v157
	v_fma_f32 v155, v155, v157, v157
	v_rcp_f32_e32 v148, v148
	v_rcp_f32_e32 v149, v149
	v_rcp_f32_e32 v150, v150
	v_rcp_f32_e32 v151, v151
	v_rcp_f32_e32 v152, v152
	v_rcp_f32_e32 v153, v153
	v_rcp_f32_e32 v154, v154
	v_rcp_f32_e32 v155, v155
	v_mul_f32_e32 v44, v44, v40
	v_mul_f32_e32 v45, v45, v41
	v_mul_f32_e32 v46, v46, v42
	v_mul_f32_e32 v47, v47, v43
	v_mul_f32_e32 v36, v36, v32
	v_mul_f32_e32 v37, v37, v33
	v_mul_f32_e32 v38, v38, v34
	v_mul_f32_e32 v39, v39, v35
	v_mul_f32_e32 v44, v44, v148
	v_mul_f32_e32 v45, v45, v149
	v_mul_f32_e32 v46, v46, v150
	v_mul_f32_e32 v47, v47, v151
	v_mul_f32_e32 v36, v36, v152
	v_mul_f32_e32 v37, v37, v153
	v_mul_f32_e32 v38, v38, v154
	v_mul_f32_e32 v39, v39, v155
	v_cvt_pk_bf16_f32 v40, v44, v45
	v_cvt_pk_bf16_f32 v41, v46, v47
	v_cvt_pk_bf16_f32 v42, v36, v37
	v_cvt_pk_bf16_f32 v43, v38, v39
	global_store_dwordx4 v[164:165], v[40:43], off
	v_mul_f32_e32 v156, 0xbfb8aa3b, v250
	v_mul_f32_e32 v158, v250, v250
	v_rcp_f32_e32 v157, v158
	v_add_u32_e32 v166, 0xa0, v138
	v_mad_i64_i32 v[164:165], s[38:39], v166, s53, v[160:161]
	v_lshl_add_u64 v[164:165], v[164:165], 0, v[162:163]
	v_mul_f32_e32 v148, v28, v156
	v_mul_f32_e32 v149, v29, v156
	v_mul_f32_e32 v150, v30, v156
	v_mul_f32_e32 v151, v31, v156
	v_mul_f32_e32 v152, v20, v156
	v_mul_f32_e32 v153, v21, v156
	v_mul_f32_e32 v154, v22, v156
	v_mul_f32_e32 v155, v23, v156
	v_exp_f32_e32 v148, v148
	v_exp_f32_e32 v149, v149
	v_exp_f32_e32 v150, v150
	v_exp_f32_e32 v151, v151
	v_exp_f32_e32 v152, v152
	v_exp_f32_e32 v153, v153
	v_exp_f32_e32 v154, v154
	v_exp_f32_e32 v155, v155
	v_fma_f32 v148, v148, v157, v157
	v_fma_f32 v149, v149, v157, v157
	v_fma_f32 v150, v150, v157, v157
	v_fma_f32 v151, v151, v157, v157
	v_fma_f32 v152, v152, v157, v157
	v_fma_f32 v153, v153, v157, v157
	v_fma_f32 v154, v154, v157, v157
	v_fma_f32 v155, v155, v157, v157
	v_rcp_f32_e32 v148, v148
	v_rcp_f32_e32 v149, v149
	v_rcp_f32_e32 v150, v150
	v_rcp_f32_e32 v151, v151
	v_rcp_f32_e32 v152, v152
	v_rcp_f32_e32 v153, v153
	v_rcp_f32_e32 v154, v154
	v_rcp_f32_e32 v155, v155
	v_mul_f32_e32 v28, v28, v24
	v_mul_f32_e32 v29, v29, v25
	v_mul_f32_e32 v30, v30, v26
	v_mul_f32_e32 v31, v31, v27
	v_mul_f32_e32 v20, v20, v16
	v_mul_f32_e32 v21, v21, v17
	v_mul_f32_e32 v22, v22, v18
	v_mul_f32_e32 v23, v23, v19
	v_mul_f32_e32 v28, v28, v148
	v_mul_f32_e32 v29, v29, v149
	v_mul_f32_e32 v30, v30, v150
	v_mul_f32_e32 v31, v31, v151
	v_mul_f32_e32 v20, v20, v152
	v_mul_f32_e32 v21, v21, v153
	v_mul_f32_e32 v22, v22, v154
	v_mul_f32_e32 v23, v23, v155
	v_cvt_pk_bf16_f32 v24, v28, v29
	v_cvt_pk_bf16_f32 v25, v30, v31
	v_cvt_pk_bf16_f32 v26, v20, v21
	v_cvt_pk_bf16_f32 v27, v22, v23
	global_store_dwordx4 v[164:165], v[24:27], off
	v_mul_f32_e32 v156, 0xbfb8aa3b, v251
	v_mul_f32_e32 v158, v251, v251
	v_rcp_f32_e32 v157, v158
	v_add_u32_e32 v166, 0xb0, v138
	v_mad_i64_i32 v[164:165], s[38:39], v166, s53, v[160:161]
	v_lshl_add_u64 v[164:165], v[164:165], 0, v[162:163]
	v_mul_f32_e32 v148, v12, v156
	v_mul_f32_e32 v149, v13, v156
	v_mul_f32_e32 v150, v14, v156
	v_mul_f32_e32 v151, v15, v156
	v_mul_f32_e32 v152, v4, v156
	v_mul_f32_e32 v153, v5, v156
	v_mul_f32_e32 v154, v6, v156
	v_mul_f32_e32 v155, v7, v156
	v_exp_f32_e32 v148, v148
	v_exp_f32_e32 v149, v149
	v_exp_f32_e32 v150, v150
	v_exp_f32_e32 v151, v151
	v_exp_f32_e32 v152, v152
	v_exp_f32_e32 v153, v153
	v_exp_f32_e32 v154, v154
	v_exp_f32_e32 v155, v155
	v_fma_f32 v148, v148, v157, v157
	v_fma_f32 v149, v149, v157, v157
	v_fma_f32 v150, v150, v157, v157
	v_fma_f32 v151, v151, v157, v157
	v_fma_f32 v152, v152, v157, v157
	v_fma_f32 v153, v153, v157, v157
	v_fma_f32 v154, v154, v157, v157
	v_fma_f32 v155, v155, v157, v157
	v_rcp_f32_e32 v148, v148
	v_rcp_f32_e32 v149, v149
	v_rcp_f32_e32 v150, v150
	v_rcp_f32_e32 v151, v151
	v_rcp_f32_e32 v152, v152
	v_rcp_f32_e32 v153, v153
	v_rcp_f32_e32 v154, v154
	v_rcp_f32_e32 v155, v155
	v_mul_f32_e32 v12, v12, v8
	v_mul_f32_e32 v13, v13, v9
	v_mul_f32_e32 v14, v14, v10
	v_mul_f32_e32 v15, v15, v11
	v_mul_f32_e32 v4, v4, v0
	v_mul_f32_e32 v5, v5, v1
	v_mul_f32_e32 v6, v6, v2
	v_mul_f32_e32 v7, v7, v3
	v_mul_f32_e32 v12, v12, v148
	v_mul_f32_e32 v13, v13, v149
	v_mul_f32_e32 v14, v14, v150
	v_mul_f32_e32 v15, v15, v151
	v_mul_f32_e32 v4, v4, v152
	v_mul_f32_e32 v5, v5, v153
	v_mul_f32_e32 v6, v6, v154
	v_mul_f32_e32 v7, v7, v155
	v_cvt_pk_bf16_f32 v8, v12, v13
	v_cvt_pk_bf16_f32 v9, v14, v15
	v_cvt_pk_bf16_f32 v10, v4, v5
	v_cvt_pk_bf16_f32 v11, v6, v7
	global_store_dwordx4 v[164:165], v[8:11], off
	s_mov_b64 s[60:61], -1
	s_andn2_b64 vcc, exec, s[40:41]
	s_cbranch_vccnz .LBB0_231
	s_andn2_b64 vcc, exec, s[46:47]
	s_cbranch_vccnz .LBB0_230
	s_barrier
	s_branch .LBB0_230

; __device__ __forceinline__ unsigned cvt_pk_bf16(float lo, float hi) { unsigned r; asm volatile("v_cvt_pk_bf16_f32 %0, %1, %2" : "=v"(r) : "v"(lo), "v"(hi)); return r; }
; __device__ __forceinline__ float fast_sigmoid(float x) { return __builtin_amdgcn_rcpf(1.f + __builtin_amdgcn_exp2f(-1.4426950408889634f * x)); }
; __device__ __forceinline__ void row_scales_direct(const float* rs, int row0, float (&rsv)[2][4]) {
; #pragma unroll
;     for (int ai = 0; ai < 2; ++ai)
; #pragma unroll
;         for (int m = 0; m < 4; ++m) rsv[ai][m] = ((const __attribute__((address_space(1))) float*)rs)[row0 + ai * HALF + m * 16];
; }
;     __device__ __forceinline__ void operator()(const f32x4 (&acc)[2][2][4][2], const Unit& u, int wr, int wc, int fr, int fq) const {
;         const int row0 = u.pm * BM + wr * 64 + fr, col0 = u.pn * HALF + wc * 32 + 8 * fq;
;         float rsv[2][4]; row_scales_direct(ssq, row0, rsv);
; #pragma unroll
;         for (int ai = 0; ai < 2; ++ai)
; #pragma unroll
;             for (int m = 0; m < 4; ++m) { float o[8];
; #pragma unroll
;                 for (int n = 0; n < 2; ++n)
; #pragma unroll
;                     for (int j = 0; j < 4; ++j) { const float g = acc[ai][0][m][n][j] * rsv[ai][m], up = acc[ai][1][m][n][j] * rsv[ai][m]; o[n * 4 + j] = g * fast_sigmoid(g) * up; }
;                 u32x4 w; w.x = cvt_pk_bf16(o[0], o[1]); w.y = cvt_pk_bf16(o[2], o[3]); w.z = cvt_pk_bf16(o[4], o[5]); w.w = cvt_pk_bf16(o[6], o[7]);
;                 *(u32x4*)(H + (size_t)(row0 + ai * HALF + m * 16) * ldh + col0) = w; }
.LBB0_1705:
	s_waitcnt vmcnt(0)
	v_mov_b32_e32 v242, v234
	v_mov_b32_e32 v243, v235
	v_mov_b32_e32 v244, v236
	v_mov_b32_e32 v245, v237
	v_mov_b32_e32 v246, v238
	v_mov_b32_e32 v247, v239
	v_mov_b32_e32 v250, v240
	v_mov_b32_e32 v251, v241
	s_and_b64 s[40:41], s[38:39], exec
	s_cselect_b32 s40, s52, s77
	v_lshl_add_u32 v166, s40, 8, v141
	v_ashrrev_i32_e32 v167, 31, v166
	v_lshl_add_u64 v[168:169], v[166:167], 2, s[46:47]
	global_load_dword v234, v[168:169], off
	global_load_dword v235, v[168:169], off offset:64
	global_load_dword v236, v[168:169], off offset:128
	global_load_dword v237, v[168:169], off offset:192
	global_load_dword v238, v[168:169], off offset:512
	global_load_dword v239, v[168:169], off offset:576
	global_load_dword v240, v[168:169], off offset:640
	global_load_dword v241, v[168:169], off offset:704
	v_lshl_add_u32 v138, s77, 8, v141
	v_lshl_or_b32 v170, s76, 7, v145
	v_ashrrev_i32_e32 v171, 31, v170
	s_movk_i32 s51, 0x2c00
	v_mov_b64_e32 v[160:161], s[44:45]
	v_lshlrev_b64 v[162:163], 1, v[170:171]
	v_mul_f32_e32 v156, 0xbfb8aa3b, v242
	v_mul_f32_e32 v158, v242, v242
	v_rcp_f32_e32 v157, v158
	v_mad_i64_i32 v[164:165], s[40:41], v138, s51, v[160:161]
	v_lshl_add_u64 v[164:165], v[164:165], 0, v[162:163]
	v_mul_f32_e32 v148, v124, v156
	v_mul_f32_e32 v149, v125, v156
	v_mul_f32_e32 v150, v126, v156
	v_mul_f32_e32 v151, v127, v156
	v_mul_f32_e32 v152, v116, v156
	v_mul_f32_e32 v153, v117, v156
	v_mul_f32_e32 v154, v118, v156
	v_mul_f32_e32 v155, v119, v156
	v_exp_f32_e32 v148, v148
	v_exp_f32_e32 v149, v149
	v_exp_f32_e32 v150, v150
	v_exp_f32_e32 v151, v151
	v_exp_f32_e32 v152, v152
	v_exp_f32_e32 v153, v153
	v_exp_f32_e32 v154, v154
	v_exp_f32_e32 v155, v155
	v_fma_f32 v148, v148, v157, v157
	v_fma_f32 v149, v149, v157, v157
	v_fma_f32 v150, v150, v157, v157
	v_fma_f32 v151, v151, v157, v157
	v_fma_f32 v152, v152, v157, v157
	v_fma_f32 v153, v153, v157, v157
	v_fma_f32 v154, v154, v157, v157
	v_fma_f32 v155, v155, v157, v157
	v_rcp_f32_e32 v148, v148
	v_rcp_f32_e32 v149, v149
	v_rcp_f32_e32 v150, v150
	v_rcp_f32_e32 v151, v151
	v_rcp_f32_e32 v152, v152
	v_rcp_f32_e32 v153, v153
	v_rcp_f32_e32 v154, v154
	v_rcp_f32_e32 v155, v155
	v_mul_f32_e32 v124, v124, v120
	v_mul_f32_e32 v125, v125, v121
	v_mul_f32_e32 v126, v126, v122
	v_mul_f32_e32 v127, v127, v123
	v_mul_f32_e32 v116, v116, v112
	v_mul_f32_e32 v117, v117, v113
	v_mul_f32_e32 v118, v118, v114
	v_mul_f32_e32 v119, v119, v115
	v_mul_f32_e32 v124, v124, v148
	v_mul_f32_e32 v125, v125, v149
	v_mul_f32_e32 v126, v126, v150
	v_mul_f32_e32 v127, v127, v151
	v_mul_f32_e32 v116, v116, v152
	v_mul_f32_e32 v117, v117, v153
	v_mul_f32_e32 v118, v118, v154
	v_mul_f32_e32 v119, v119, v155
	v_cvt_pk_bf16_f32 v120, v124, v125
	v_cvt_pk_bf16_f32 v121, v126, v127
	v_cvt_pk_bf16_f32 v122, v116, v117
	v_cvt_pk_bf16_f32 v123, v118, v119
	global_store_dwordx4 v[164:165], v[120:123], off
	v_mul_f32_e32 v156, 0xbfb8aa3b, v243
	v_mul_f32_e32 v158, v243, v243
	v_rcp_f32_e32 v157, v158
	v_add_u32_e32 v166, 0x10, v138
	v_mad_i64_i32 v[164:165], s[40:41], v166, s51, v[160:161]
	v_lshl_add_u64 v[164:165], v[164:165], 0, v[162:163]
	v_mul_f32_e32 v148, v108, v156
	v_mul_f32_e32 v149, v109, v156
	v_mul_f32_e32 v150, v110, v156
	v_mul_f32_e32 v151, v111, v156
	v_mul_f32_e32 v152, v100, v156
	v_mul_f32_e32 v153, v101, v156
	v_mul_f32_e32 v154, v102, v156
	v_mul_f32_e32 v155, v103, v156
	v_exp_f32_e32 v148, v148
	v_exp_f32_e32 v149, v149
	v_exp_f32_e32 v150, v150
	v_exp_f32_e32 v151, v151
	v_exp_f32_e32 v152, v152
	v_exp_f32_e32 v153, v153
	v_exp_f32_e32 v154, v154
	v_exp_f32_e32 v155, v155
	v_fma_f32 v148, v148, v157, v157
	v_fma_f32 v149, v149, v157, v157
	v_fma_f32 v150, v150, v157, v157
	v_fma_f32 v151, v151, v157, v157
	v_fma_f32 v152, v152, v157, v157
	v_fma_f32 v153, v153, v157, v157
	v_fma_f32 v154, v154, v157, v157
	v_fma_f32 v155, v155, v157, v157
	v_rcp_f32_e32 v148, v148
	v_rcp_f32_e32 v149, v149
	v_rcp_f32_e32 v150, v150
	v_rcp_f32_e32 v151, v151
	v_rcp_f32_e32 v152, v152
	v_rcp_f32_e32 v153, v153
	v_rcp_f32_e32 v154, v154
	v_rcp_f32_e32 v155, v155
	v_mul_f32_e32 v108, v108, v104
	v_mul_f32_e32 v109, v109, v105
	v_mul_f32_e32 v110, v110, v106
	v_mul_f32_e32 v111, v111, v107
	v_mul_f32_e32 v100, v100, v96
	v_mul_f32_e32 v101, v101, v97
	v_mul_f32_e32 v102, v102, v98
	v_mul_f32_e32 v103, v103, v99
	v_mul_f32_e32 v108, v108, v148
	v_mul_f32_e32 v109, v109, v149
	v_mul_f32_e32 v110, v110, v150
	v_mul_f32_e32 v111, v111, v151
	v_mul_f32_e32 v100, v100, v152
	v_mul_f32_e32 v101, v101, v153
	v_mul_f32_e32 v102, v102, v154
	v_mul_f32_e32 v103, v103, v155
	v_cvt_pk_bf16_f32 v104, v108, v109
	v_cvt_pk_bf16_f32 v105, v110, v111
	v_cvt_pk_bf16_f32 v106, v100, v101
	v_cvt_pk_bf16_f32 v107, v102, v103
	global_store_dwordx4 v[164:165], v[104:107], off
	v_mul_f32_e32 v156, 0xbfb8aa3b, v244
	v_mul_f32_e32 v158, v244, v244
	v_rcp_f32_e32 v157, v158
	v_add_u32_e32 v166, 0x20, v138
	v_mad_i64_i32 v[164:165], s[40:41], v166, s51, v[160:161]
	v_lshl_add_u64 v[164:165], v[164:165], 0, v[162:163]
	v_mul_f32_e32 v148, v92, v156
	v_mul_f32_e32 v149, v93, v156
	v_mul_f32_e32 v150, v94, v156
	v_mul_f32_e32 v151, v95, v156
	v_mul_f32_e32 v152, v84, v156
	v_mul_f32_e32 v153, v85, v156
	v_mul_f32_e32 v154, v86, v156
	v_mul_f32_e32 v155, v87, v156
	v_exp_f32_e32 v148, v148
	v_exp_f32_e32 v149, v149
	v_exp_f32_e32 v150, v150
	v_exp_f32_e32 v151, v151
	v_exp_f32_e32 v152, v152
	v_exp_f32_e32 v153, v153
	v_exp_f32_e32 v154, v154
	v_exp_f32_e32 v155, v155
	v_fma_f32 v148, v148, v157, v157
	v_fma_f32 v149, v149, v157, v157
	v_fma_f32 v150, v150, v157, v157
	v_fma_f32 v151, v151, v157, v157
	v_fma_f32 v152, v152, v157, v157
; __device__ __forceinline__ unsigned cvt_pk_bf16(float lo, float hi) { unsigned r; asm volatile("v_cvt_pk_bf16_f32 %0, %1, %2" : "=v"(r) : "v"(lo), "v"(hi)); return r; }
; __device__ __forceinline__ float fast_sigmoid(float x) { return __builtin_amdgcn_rcpf(1.f + __builtin_amdgcn_exp2f(-1.4426950408889634f * x)); }
;     __device__ __forceinline__ void operator()(const f32x4 (&acc)[2][2][4][2], const Unit& u, int wr, int wc, int fr, int fq) const {
;     ...
;             for (int m = 0; m < 4; ++m) { float o[8];
; #pragma unroll
;                 for (int n = 0; n < 2; ++n)
; #pragma unroll
;                     for (int j = 0; j < 4; ++j) { const float g = acc[ai][0][m][n][j] * rsv[ai][m], up = acc[ai][1][m][n][j] * rsv[ai][m]; o[n * 4 + j] = g * fast_sigmoid(g) * up; }
;                 u32x4 w; w.x = cvt_pk_bf16(o[0], o[1]); w.y = cvt_pk_bf16(o[2], o[3]); w.z = cvt_pk_bf16(o[4], o[5]); w.w = cvt_pk_bf16(o[6], o[7]);
;                 *(u32x4*)(H + (size_t)(row0 + ai * HALF + m * 16) * ldh + col0) = w; }
	v_fma_f32 v153, v153, v157, v157
	v_fma_f32 v154, v154, v157, v157
	v_fma_f32 v155, v155, v157, v157
	v_rcp_f32_e32 v148, v148
	v_rcp_f32_e32 v149, v149
	v_rcp_f32_e32 v150, v150
	v_rcp_f32_e32 v151, v151
	v_rcp_f32_e32 v152, v152
	v_rcp_f32_e32 v153, v153
	v_rcp_f32_e32 v154, v154
	v_rcp_f32_e32 v155, v155
	v_mul_f32_e32 v92, v92, v88
	v_mul_f32_e32 v93, v93, v89
	v_mul_f32_e32 v94, v94, v90
	v_mul_f32_e32 v95, v95, v91
	v_mul_f32_e32 v84, v84, v80
	v_mul_f32_e32 v85, v85, v81
	v_mul_f32_e32 v86, v86, v82
	v_mul_f32_e32 v87, v87, v83
	v_mul_f32_e32 v92, v92, v148
	v_mul_f32_e32 v93, v93, v149
	v_mul_f32_e32 v94, v94, v150
	v_mul_f32_e32 v95, v95, v151
	v_mul_f32_e32 v84, v84, v152
	v_mul_f32_e32 v85, v85, v153
	v_mul_f32_e32 v86, v86, v154
	v_mul_f32_e32 v87, v87, v155
	v_cvt_pk_bf16_f32 v88, v92, v93
	v_cvt_pk_bf16_f32 v89, v94, v95
	v_cvt_pk_bf16_f32 v90, v84, v85
	v_cvt_pk_bf16_f32 v91, v86, v87
	global_store_dwordx4 v[164:165], v[88:91], off
	v_mul_f32_e32 v156, 0xbfb8aa3b, v245
	v_mul_f32_e32 v158, v245, v245
	v_rcp_f32_e32 v157, v158
	v_add_u32_e32 v166, 0x30, v138
	v_mad_i64_i32 v[164:165], s[40:41], v166, s51, v[160:161]
	v_lshl_add_u64 v[164:165], v[164:165], 0, v[162:163]
	v_mul_f32_e32 v148, v76, v156
	v_mul_f32_e32 v149, v77, v156
	v_mul_f32_e32 v150, v78, v156
	v_mul_f32_e32 v151, v79, v156
	v_mul_f32_e32 v152, v68, v156
	v_mul_f32_e32 v153, v69, v156
	v_mul_f32_e32 v154, v70, v156
	v_mul_f32_e32 v155, v71, v156
	v_exp_f32_e32 v148, v148
	v_exp_f32_e32 v149, v149
	v_exp_f32_e32 v150, v150
	v_exp_f32_e32 v151, v151
	v_exp_f32_e32 v152, v152
	v_exp_f32_e32 v153, v153
	v_exp_f32_e32 v154, v154
	v_exp_f32_e32 v155, v155
	v_fma_f32 v148, v148, v157, v157
	v_fma_f32 v149, v149, v157, v157
	v_fma_f32 v150, v150, v157, v157
	v_fma_f32 v151, v151, v157, v157
	v_fma_f32 v152, v152, v157, v157
	v_fma_f32 v153, v153, v157, v157
	v_fma_f32 v154, v154, v157, v157
	v_fma_f32 v155, v155, v157, v157
	v_rcp_f32_e32 v148, v148
	v_rcp_f32_e32 v149, v149
	v_rcp_f32_e32 v150, v150
	v_rcp_f32_e32 v151, v151
	v_rcp_f32_e32 v152, v152
	v_rcp_f32_e32 v153, v153
	v_rcp_f32_e32 v154, v154
	v_rcp_f32_e32 v155, v155
	v_mul_f32_e32 v76, v76, v72
	v_mul_f32_e32 v77, v77, v73
	v_mul_f32_e32 v78, v78, v74
	v_mul_f32_e32 v79, v79, v75
	v_mul_f32_e32 v68, v68, v64
	v_mul_f32_e32 v69, v69, v65
	v_mul_f32_e32 v70, v70, v66
	v_mul_f32_e32 v71, v71, v67
	v_mul_f32_e32 v76, v76, v148
	v_mul_f32_e32 v77, v77, v149
	v_mul_f32_e32 v78, v78, v150
	v_mul_f32_e32 v79, v79, v151
	v_mul_f32_e32 v68, v68, v152
	v_mul_f32_e32 v69, v69, v153
	v_mul_f32_e32 v70, v70, v154
	v_mul_f32_e32 v71, v71, v155
	v_cvt_pk_bf16_f32 v72, v76, v77
	v_cvt_pk_bf16_f32 v73, v78, v79
	v_cvt_pk_bf16_f32 v74, v68, v69
	v_cvt_pk_bf16_f32 v75, v70, v71
	global_store_dwordx4 v[164:165], v[72:75], off
	v_mul_f32_e32 v156, 0xbfb8aa3b, v246
	v_mul_f32_e32 v158, v246, v246
	v_rcp_f32_e32 v157, v158
	v_add_u32_e32 v166, 0x80, v138
	v_mad_i64_i32 v[164:165], s[40:41], v166, s51, v[160:161]
	v_lshl_add_u64 v[164:165], v[164:165], 0, v[162:163]
	v_mul_f32_e32 v148, v60, v156
	v_mul_f32_e32 v149, v61, v156
	v_mul_f32_e32 v150, v62, v156
	v_mul_f32_e32 v151, v63, v156
	v_mul_f32_e32 v152, v52, v156
	v_mul_f32_e32 v153, v53, v156
	v_mul_f32_e32 v154, v54, v156
	v_mul_f32_e32 v155, v55, v156
	v_exp_f32_e32 v148, v148
	v_exp_f32_e32 v149, v149
	v_exp_f32_e32 v150, v150
	v_exp_f32_e32 v151, v151
	v_exp_f32_e32 v152, v152
	v_exp_f32_e32 v153, v153
	v_exp_f32_e32 v154, v154
	v_exp_f32_e32 v155, v155
	v_fma_f32 v148, v148, v157, v157
	v_fma_f32 v149, v149, v157, v157
	v_fma_f32 v150, v150, v157, v157
	v_fma_f32 v151, v151, v157, v157
	v_fma_f32 v152, v152, v157, v157
	v_fma_f32 v153, v153, v157, v157
	v_fma_f32 v154, v154, v157, v157
	v_fma_f32 v155, v155, v157, v157
	v_rcp_f32_e32 v148, v148
	v_rcp_f32_e32 v149, v149
	v_rcp_f32_e32 v150, v150
	v_rcp_f32_e32 v151, v151
	v_rcp_f32_e32 v152, v152
	v_rcp_f32_e32 v153, v153
	v_rcp_f32_e32 v154, v154
	v_rcp_f32_e32 v155, v155
	v_mul_f32_e32 v60, v60, v56
	v_mul_f32_e32 v61, v61, v57
	v_mul_f32_e32 v62, v62, v58
	v_mul_f32_e32 v63, v63, v59
	v_mul_f32_e32 v52, v52, v48
	v_mul_f32_e32 v53, v53, v49
	v_mul_f32_e32 v54, v54, v50
	v_mul_f32_e32 v55, v55, v51
	v_mul_f32_e32 v60, v60, v148
	v_mul_f32_e32 v61, v61, v149
	v_mul_f32_e32 v62, v62, v150
	v_mul_f32_e32 v63, v63, v151
	v_mul_f32_e32 v52, v52, v152
	v_mul_f32_e32 v53, v53, v153
	v_mul_f32_e32 v54, v54, v154
	v_mul_f32_e32 v55, v55, v155
	v_cvt_pk_bf16_f32 v56, v60, v61
	v_cvt_pk_bf16_f32 v57, v62, v63
	v_cvt_pk_bf16_f32 v58, v52, v53
	v_cvt_pk_bf16_f32 v59, v54, v55
	global_store_dwordx4 v[164:165], v[56:59], off
	v_mul_f32_e32 v156, 0xbfb8aa3b, v247
	v_mul_f32_e32 v158, v247, v247
	v_rcp_f32_e32 v157, v158
	v_add_u32_e32 v166, 0x90, v138
	v_mad_i64_i32 v[164:165], s[40:41], v166, s51, v[160:161]
	v_lshl_add_u64 v[164:165], v[164:165], 0, v[162:163]
	v_mul_f32_e32 v148, v44, v156
	v_mul_f32_e32 v149, v45, v156
	v_mul_f32_e32 v150, v46, v156
	v_mul_f32_e32 v151, v47, v156
	v_mul_f32_e32 v152, v36, v156
	v_mul_f32_e32 v153, v37, v156
	v_mul_f32_e32 v154, v38, v156
	v_mul_f32_e32 v155, v39, v156
	v_exp_f32_e32 v148, v148
; __device__ __forceinline__ unsigned cvt_pk_bf16(float lo, float hi) { unsigned r; asm volatile("v_cvt_pk_bf16_f32 %0, %1, %2" : "=v"(r) : "v"(lo), "v"(hi)); return r; }
; __device__ __forceinline__ float fast_sigmoid(float x) { return __builtin_amdgcn_rcpf(1.f + __builtin_amdgcn_exp2f(-1.4426950408889634f * x)); }
; #define PG8_BAR __builtin_amdgcn_s_barrier()
;     __device__ __forceinline__ void operator()(const f32x4 (&acc)[2][2][4][2], const Unit& u, int wr, int wc, int fr, int fq) const {
;     ...
;             for (int m = 0; m < 4; ++m) { float o[8];
; #pragma unroll
;                 for (int n = 0; n < 2; ++n)
; #pragma unroll
;                     for (int j = 0; j < 4; ++j) { const float g = acc[ai][0][m][n][j] * rsv[ai][m], up = acc[ai][1][m][n][j] * rsv[ai][m]; o[n * 4 + j] = g * fast_sigmoid(g) * up; }
;                 u32x4 w; w.x = cvt_pk_bf16(o[0], o[1]); w.y = cvt_pk_bf16(o[2], o[3]); w.z = cvt_pk_bf16(o[4], o[5]); w.w = cvt_pk_bf16(o[6], o[7]);
;                 *(u32x4*)(H + (size_t)(row0 + ai * HALF + m * 16) * ldh + col0) = w; }
; template <class Epi, class Sched, bool ALIGN_EPI = false, bool SP2 = false>
; __device__ __forceinline__ void gemm_phase(PG8_LAS unsigned char* lds, const Gemm g, const Sched& S, const Epi& E, int wave_id) {
;     ...
;         if constexpr (!Epi::AFTER_DRAIN) { E(acc, cur, wr, wc, fr, fq); S.done(cur); }
;         if (!has_next) break;
; #pragma unroll
;         for (int a = 0; a < 2; ++a)
; #pragma unroll
;             for (int b = 0; b < 2; ++b)
; #pragma unroll
;                 for (int m = 0; m < 4; ++m)
; #pragma unroll
;                     for (int n = 0; n < 2; ++n) acc[a][b][m][n] = (f32x4){0.f, 0.f, 0.f, 0.f};
;         cur = nxt; cA = nA; cB = nB; ++ui;
;         if constexpr (ALIGN_EPI) { if (wr == 1) PG8_BAR; }
	v_exp_f32_e32 v149, v149
	v_exp_f32_e32 v150, v150
	v_exp_f32_e32 v151, v151
	v_exp_f32_e32 v152, v152
	v_exp_f32_e32 v153, v153
	v_exp_f32_e32 v154, v154
	v_exp_f32_e32 v155, v155
	v_fma_f32 v148, v148, v157, v157
	v_fma_f32 v149, v149, v157, v157
	v_fma_f32 v150, v150, v157, v157
	v_fma_f32 v151, v151, v157, v157
	v_fma_f32 v152, v152, v157, v157
	v_fma_f32 v153, v153, v157, v157
	v_fma_f32 v154, v154, v157, v157
	v_fma_f32 v155, v155, v157, v157
	v_rcp_f32_e32 v148, v148
	v_rcp_f32_e32 v149, v149
	v_rcp_f32_e32 v150, v150
	v_rcp_f32_e32 v151, v151
	v_rcp_f32_e32 v152, v152
	v_rcp_f32_e32 v153, v153
	v_rcp_f32_e32 v154, v154
	v_rcp_f32_e32 v155, v155
	v_mul_f32_e32 v44, v44, v40
	v_mul_f32_e32 v45, v45, v41
	v_mul_f32_e32 v46, v46, v42
	v_mul_f32_e32 v47, v47, v43
	v_mul_f32_e32 v36, v36, v32
	v_mul_f32_e32 v37, v37, v33
	v_mul_f32_e32 v38, v38, v34
	v_mul_f32_e32 v39, v39, v35
	v_mul_f32_e32 v44, v44, v148
	v_mul_f32_e32 v45, v45, v149
	v_mul_f32_e32 v46, v46, v150
	v_mul_f32_e32 v47, v47, v151
	v_mul_f32_e32 v36, v36, v152
	v_mul_f32_e32 v37, v37, v153
	v_mul_f32_e32 v38, v38, v154
	v_mul_f32_e32 v39, v39, v155
	v_cvt_pk_bf16_f32 v40, v44, v45
	v_cvt_pk_bf16_f32 v41, v46, v47
	v_cvt_pk_bf16_f32 v42, v36, v37
	v_cvt_pk_bf16_f32 v43, v38, v39
	global_store_dwordx4 v[164:165], v[40:43], off
	v_mul_f32_e32 v156, 0xbfb8aa3b, v250
	v_mul_f32_e32 v158, v250, v250
	v_rcp_f32_e32 v157, v158
	v_add_u32_e32 v166, 0xa0, v138
	v_mad_i64_i32 v[164:165], s[40:41], v166, s51, v[160:161]
	v_lshl_add_u64 v[164:165], v[164:165], 0, v[162:163]
	v_mul_f32_e32 v148, v28, v156
	v_mul_f32_e32 v149, v29, v156
	v_mul_f32_e32 v150, v30, v156
	v_mul_f32_e32 v151, v31, v156
	v_mul_f32_e32 v152, v20, v156
	v_mul_f32_e32 v153, v21, v156
	v_mul_f32_e32 v154, v22, v156
	v_mul_f32_e32 v155, v23, v156
	v_exp_f32_e32 v148, v148
	v_exp_f32_e32 v149, v149
	v_exp_f32_e32 v150, v150
	v_exp_f32_e32 v151, v151
	v_exp_f32_e32 v152, v152
	v_exp_f32_e32 v153, v153
	v_exp_f32_e32 v154, v154
	v_exp_f32_e32 v155, v155
	v_fma_f32 v148, v148, v157, v157
	v_fma_f32 v149, v149, v157, v157
	v_fma_f32 v150, v150, v157, v157
	v_fma_f32 v151, v151, v157, v157
	v_fma_f32 v152, v152, v157, v157
	v_fma_f32 v153, v153, v157, v157
	v_fma_f32 v154, v154, v157, v157
	v_fma_f32 v155, v155, v157, v157
	v_rcp_f32_e32 v148, v148
	v_rcp_f32_e32 v149, v149
	v_rcp_f32_e32 v150, v150
	v_rcp_f32_e32 v151, v151
	v_rcp_f32_e32 v152, v152
	v_rcp_f32_e32 v153, v153
	v_rcp_f32_e32 v154, v154
	v_rcp_f32_e32 v155, v155
	v_mul_f32_e32 v28, v28, v24
	v_mul_f32_e32 v29, v29, v25
	v_mul_f32_e32 v30, v30, v26
	v_mul_f32_e32 v31, v31, v27
	v_mul_f32_e32 v20, v20, v16
	v_mul_f32_e32 v21, v21, v17
	v_mul_f32_e32 v22, v22, v18
	v_mul_f32_e32 v23, v23, v19
	v_mul_f32_e32 v28, v28, v148
	v_mul_f32_e32 v29, v29, v149
	v_mul_f32_e32 v30, v30, v150
	v_mul_f32_e32 v31, v31, v151
	v_mul_f32_e32 v20, v20, v152
	v_mul_f32_e32 v21, v21, v153
	v_mul_f32_e32 v22, v22, v154
	v_mul_f32_e32 v23, v23, v155
	v_cvt_pk_bf16_f32 v24, v28, v29
	v_cvt_pk_bf16_f32 v25, v30, v31
	v_cvt_pk_bf16_f32 v26, v20, v21
	v_cvt_pk_bf16_f32 v27, v22, v23
	global_store_dwordx4 v[164:165], v[24:27], off
	v_mul_f32_e32 v156, 0xbfb8aa3b, v251
	v_mul_f32_e32 v158, v251, v251
	v_rcp_f32_e32 v157, v158
	v_add_u32_e32 v166, 0xb0, v138
	v_mad_i64_i32 v[164:165], s[40:41], v166, s51, v[160:161]
	v_lshl_add_u64 v[164:165], v[164:165], 0, v[162:163]
	v_mul_f32_e32 v148, v12, v156
	v_mul_f32_e32 v149, v13, v156
	v_mul_f32_e32 v150, v14, v156
	v_mul_f32_e32 v151, v15, v156
	v_mul_f32_e32 v152, v4, v156
	v_mul_f32_e32 v153, v5, v156
	v_mul_f32_e32 v154, v6, v156
	v_mul_f32_e32 v155, v7, v156
	v_exp_f32_e32 v148, v148
	v_exp_f32_e32 v149, v149
	v_exp_f32_e32 v150, v150
	v_exp_f32_e32 v151, v151
	v_exp_f32_e32 v152, v152
	v_exp_f32_e32 v153, v153
	v_exp_f32_e32 v154, v154
	v_exp_f32_e32 v155, v155
	v_fma_f32 v148, v148, v157, v157
	v_fma_f32 v149, v149, v157, v157
	v_fma_f32 v150, v150, v157, v157
	v_fma_f32 v151, v151, v157, v157
	v_fma_f32 v152, v152, v157, v157
	v_fma_f32 v153, v153, v157, v157
	v_fma_f32 v154, v154, v157, v157
	v_fma_f32 v155, v155, v157, v157
	v_rcp_f32_e32 v148, v148
	v_rcp_f32_e32 v149, v149
	v_rcp_f32_e32 v150, v150
	v_rcp_f32_e32 v151, v151
	v_rcp_f32_e32 v152, v152
	v_rcp_f32_e32 v153, v153
	v_rcp_f32_e32 v154, v154
	v_rcp_f32_e32 v155, v155
	v_mul_f32_e32 v12, v12, v8
	v_mul_f32_e32 v13, v13, v9
	v_mul_f32_e32 v14, v14, v10
	v_mul_f32_e32 v15, v15, v11
	v_mul_f32_e32 v4, v4, v0
	v_mul_f32_e32 v5, v5, v1
	v_mul_f32_e32 v6, v6, v2
	v_mul_f32_e32 v7, v7, v3
	v_mul_f32_e32 v12, v12, v148
	v_mul_f32_e32 v13, v13, v149
	v_mul_f32_e32 v14, v14, v150
	v_mul_f32_e32 v15, v15, v151
	v_mul_f32_e32 v4, v4, v152
	v_mul_f32_e32 v5, v5, v153
	v_mul_f32_e32 v6, v6, v154
	v_mul_f32_e32 v7, v7, v155
	v_cvt_pk_bf16_f32 v8, v12, v13
	v_cvt_pk_bf16_f32 v9, v14, v15
	v_cvt_pk_bf16_f32 v10, v4, v5
	v_cvt_pk_bf16_f32 v11, v6, v7
	global_store_dwordx4 v[164:165], v[8:11], off
	s_mov_b64 s[58:59], -1
	s_andn2_b64 vcc, exec, s[38:39]
	s_cbranch_vccnz .LBB0_1698
	s_andn2_b64 vcc, exec, s[42:43]
	s_cbranch_vccnz .LBB0_1697
	s_barrier
	s_branch .LBB0_1697
